# cache-policy hint: nt on the FFN1-in / FFN2-in SwiGLU epilogue stores (act is consumed from beyond L2 anyway; keep L2 for the GEMM operands), on v51
# baseline (speedup 1.0000x reference)
.Lrs_done1:
	v_pk_mul_f32 v[126:127], v[126:127], v[150:151] op_sel_hi:[1,0]
	v_pk_mul_f32 v[122:123], v[122:123], v[150:151] op_sel_hi:[1,0]
	v_pk_mul_f32 v[124:125], v[124:125], v[150:151] op_sel_hi:[1,0]
	v_pk_mul_f32 v[122:123], v[126:127], v[122:123]
	v_mul_f32_e32 v139, 0xbfb8aa3b, v126
	v_mul_f32_e32 v126, 0xbfb8aa3b, v127
	v_exp_f32_e32 v126, v126
	v_exp_f32_e32 v139, v139
	v_pk_mul_f32 v[118:119], v[118:119], v[150:151] op_sel_hi:[1,0]
	v_pk_mul_f32 v[114:115], v[114:115], v[150:151] op_sel_hi:[1,0]
	v_add_f32_e32 v126, 1.0, v126
	v_rcp_f32_e32 v157, v126
	v_pk_mul_f32 v[126:127], v[128:129], v[150:151] op_sel_hi:[1,0]
	v_add_f32_e32 v139, 1.0, v139
	v_mul_f32_e32 v128, 0xbfb8aa3b, v126
	v_pk_mul_f32 v[124:125], v[126:127], v[124:125]
	v_mul_f32_e32 v126, 0xbfb8aa3b, v127
	v_exp_f32_e32 v128, v128
	v_exp_f32_e32 v126, v126
	v_rcp_f32_e32 v156, v139
	v_pk_mul_f32 v[114:115], v[118:119], v[114:115]
	v_add_f32_e32 v128, 1.0, v128
	v_add_f32_e32 v126, 1.0, v126
	v_rcp_f32_e32 v128, v128
	v_rcp_f32_e32 v129, v126
	v_pk_mul_f32 v[122:123], v[122:123], v[156:157]
	v_pk_mul_f32 v[116:117], v[116:117], v[150:151] op_sel_hi:[1,0]
	v_cvt_pk_bf16_f32 v122, v122, v123
	v_pk_mul_f32 v[124:125], v[124:125], v[128:129]
	v_lshl_or_b32 v152, s18, 7, v175
	v_cvt_pk_bf16_f32 v123, v124, v125
	v_mul_f32_e32 v124, 0xbfb8aa3b, v118
	v_mul_f32_e32 v118, 0xbfb8aa3b, v119
	v_exp_f32_e32 v118, v118
	v_exp_f32_e32 v124, v124
	s_movk_i32 s6, 0xb00
	v_pk_mul_f32 v[110:111], v[110:111], v[48:49] op_sel_hi:[1,0]
	v_add_f32_e32 v118, 1.0, v118
	v_rcp_f32_e32 v125, v118
	v_pk_mul_f32 v[118:119], v[120:121], v[150:151] op_sel_hi:[1,0]
	v_add_f32_e32 v124, 1.0, v124
	v_mul_f32_e32 v120, 0xbfb8aa3b, v118
	v_pk_mul_f32 v[116:117], v[118:119], v[116:117]
	v_mul_f32_e32 v118, 0xbfb8aa3b, v119
	v_exp_f32_e32 v120, v120
	v_exp_f32_e32 v118, v118
	v_rcp_f32_e32 v124, v124
	v_pk_mul_f32 v[106:107], v[106:107], v[48:49] op_sel_hi:[1,0]
	v_add_f32_e32 v120, 1.0, v120
	v_add_f32_e32 v118, 1.0, v118
	v_rcp_f32_e32 v120, v120
	v_rcp_f32_e32 v121, v118
	v_pk_mul_f32 v[114:115], v[114:115], v[124:125]
	v_pk_mul_f32 v[106:107], v[110:111], v[106:107]
	v_cvt_pk_bf16_f32 v124, v114, v115
	v_mad_u64_u32 v[114:115], s[20:21], v177, s6, v[152:153]
	v_pk_mul_f32 v[116:117], v[116:117], v[120:121]
	v_mov_b32_e32 v115, v49
	v_cvt_pk_bf16_f32 v125, v116, v117
	v_lshl_add_u64 v[116:117], v[114:115], 1, s[12:13]
	v_mul_f32_e32 v115, 0xbfb8aa3b, v110
	v_mul_f32_e32 v110, 0xbfb8aa3b, v111
	v_exp_f32_e32 v110, v110
	global_store_dwordx4 v[116:117], v[122:125], off nt
	s_nop 1
	v_pk_mul_f32 v[108:109], v[108:109], v[48:49] op_sel_hi:[1,0]
	v_exp_f32_e32 v115, v115
	v_add_f32_e32 v110, 1.0, v110
	v_rcp_f32_e32 v117, v110
	v_pk_mul_f32 v[110:111], v[112:113], v[48:49] op_sel_hi:[1,0]
	v_add_f32_e32 v115, 1.0, v115
	v_mul_f32_e32 v112, 0xbfb8aa3b, v110
	v_pk_mul_f32 v[108:109], v[110:111], v[108:109]
	v_mul_f32_e32 v110, 0xbfb8aa3b, v111
	v_exp_f32_e32 v112, v112
	v_exp_f32_e32 v110, v110
	v_rcp_f32_e32 v116, v115
	v_pk_mul_f32 v[102:103], v[102:103], v[48:49] op_sel_hi:[1,0]
	v_add_f32_e32 v112, 1.0, v112
	v_add_f32_e32 v110, 1.0, v110
	v_rcp_f32_e32 v112, v112
	v_rcp_f32_e32 v113, v110
	v_pk_mul_f32 v[106:107], v[106:107], v[116:117]
	v_pk_mul_f32 v[98:99], v[98:99], v[48:49] op_sel_hi:[1,0]
	v_cvt_pk_bf16_f32 v106, v106, v107
	v_pk_mul_f32 v[108:109], v[108:109], v[112:113]
	v_pk_mul_f32 v[98:99], v[102:103], v[98:99]
	v_cvt_pk_bf16_f32 v107, v108, v109
	v_mul_f32_e32 v108, 0xbfb8aa3b, v102
	v_mul_f32_e32 v102, 0xbfb8aa3b, v103
	v_exp_f32_e32 v102, v102
	v_exp_f32_e32 v108, v108
	v_pk_mul_f32 v[100:101], v[100:101], v[48:49] op_sel_hi:[1,0]
	v_pk_mul_f32 v[94:95], v[94:95], v[148:149] op_sel_hi:[1,0]
	v_add_f32_e32 v102, 1.0, v102
	v_rcp_f32_e32 v109, v102
	v_pk_mul_f32 v[102:103], v[104:105], v[48:49] op_sel_hi:[1,0]
	v_add_f32_e32 v108, 1.0, v108
	v_mul_f32_e32 v48, 0xbfb8aa3b, v103
	v_exp_f32_e32 v48, v48
	v_rcp_f32_e32 v108, v108
	v_mul_f32_e32 v104, 0xbfb8aa3b, v102
	v_exp_f32_e32 v104, v104
	v_add_f32_e32 v48, 1.0, v48
	v_pk_mul_f32 v[98:99], v[98:99], v[108:109]
	v_rcp_f32_e32 v105, v48
	v_add_u32_e32 v48, 0xb000, v114
	v_add_f32_e32 v104, 1.0, v104
	v_cvt_pk_bf16_f32 v108, v98, v99
	v_lshl_add_u64 v[98:99], v[48:49], 1, s[12:13]
	v_mul_f32_e32 v48, 0xbfb8aa3b, v94
	v_rcp_f32_e32 v104, v104
	v_exp_f32_e32 v48, v48
	v_pk_mul_f32 v[100:101], v[102:103], v[100:101]
	v_pk_mul_f32 v[90:91], v[90:91], v[148:149] op_sel_hi:[1,0]
	v_pk_mul_f32 v[100:101], v[100:101], v[104:105]
	v_add_f32_e32 v48, 1.0, v48
	v_cvt_pk_bf16_f32 v109, v100, v101
	global_store_dwordx4 v[98:99], v[106:109], off nt
	s_nop 1
	v_rcp_f32_e32 v98, v48
	v_mul_f32_e32 v48, 0xbfb8aa3b, v95
	v_exp_f32_e32 v48, v48
	v_pk_mul_f32 v[90:91], v[94:95], v[90:91]
	v_pk_mul_f32 v[94:95], v[96:97], v[148:149] op_sel_hi:[1,0]
	v_pk_mul_f32 v[86:87], v[86:87], v[148:149] op_sel_hi:[1,0]
	v_add_f32_e32 v48, 1.0, v48
	v_rcp_f32_e32 v99, v48
	v_mul_f32_e32 v48, 0xbfb8aa3b, v94
	v_exp_f32_e32 v48, v48
	v_pk_mul_f32 v[92:93], v[92:93], v[148:149] op_sel_hi:[1,0]
	v_pk_mul_f32 v[90:91], v[90:91], v[98:99]
	v_pk_mul_f32 v[92:93], v[94:95], v[92:93]
	v_add_f32_e32 v48, 1.0, v48
	v_rcp_f32_e32 v96, v48
	v_mul_f32_e32 v48, 0xbfb8aa3b, v95
	v_exp_f32_e32 v48, v48
	v_cvt_pk_bf16_f32 v90, v90, v91
	v_pk_mul_f32 v[82:83], v[82:83], v[148:149] op_sel_hi:[1,0]
	v_pk_mul_f32 v[78:79], v[78:79], v[146:147] op_sel_hi:[1,0]
	v_add_f32_e32 v48, 1.0, v48
	v_rcp_f32_e32 v97, v48
	v_mul_f32_e32 v48, 0xbfb8aa3b, v86
	v_exp_f32_e32 v48, v48
	v_pk_mul_f32 v[82:83], v[86:87], v[82:83]
	v_pk_mul_f32 v[92:93], v[92:93], v[96:97]
	v_pk_mul_f32 v[84:85], v[84:85], v[148:149] op_sel_hi:[1,0]
	v_add_f32_e32 v48, 1.0, v48
	v_cvt_pk_bf16_f32 v91, v92, v93
	v_rcp_f32_e32 v92, v48
	v_mul_f32_e32 v48, 0xbfb8aa3b, v87
	v_exp_f32_e32 v48, v48
	v_pk_mul_f32 v[86:87], v[88:89], v[148:149] op_sel_hi:[1,0]
	v_pk_mul_f32 v[74:75], v[74:75], v[146:147] op_sel_hi:[1,0]
	v_pk_mul_f32 v[84:85], v[86:87], v[84:85]
	v_add_f32_e32 v48, 1.0, v48
	v_rcp_f32_e32 v93, v48
	v_mul_f32_e32 v48, 0xbfb8aa3b, v86
	v_exp_f32_e32 v48, v48
	v_pk_mul_f32 v[74:75], v[78:79], v[74:75]
	v_pk_mul_f32 v[82:83], v[82:83], v[92:93]
	v_pk_mul_f32 v[70:71], v[70:71], v[146:147] op_sel_hi:[1,0]
	v_add_f32_e32 v48, 1.0, v48
	v_rcp_f32_e32 v88, v48
	v_mul_f32_e32 v48, 0xbfb8aa3b, v87
	v_exp_f32_e32 v48, v48
	v_cvt_pk_bf16_f32 v92, v82, v83
	v_pk_mul_f32 v[76:77], v[76:77], v[146:147] op_sel_hi:[1,0]
	v_pk_mul_f32 v[66:67], v[66:67], v[146:147] op_sel_hi:[1,0]
	v_add_f32_e32 v48, 1.0, v48
	v_rcp_f32_e32 v89, v48
	v_add_u32_e32 v48, 0x16000, v114
	v_lshl_add_u64 v[82:83], v[48:49], 1, s[12:13]
	v_mul_f32_e32 v48, 0xbfb8aa3b, v78
	v_exp_f32_e32 v48, v48
	v_pk_mul_f32 v[84:85], v[84:85], v[88:89]
	v_pk_mul_f32 v[66:67], v[70:71], v[66:67]
	v_cvt_pk_bf16_f32 v93, v84, v85
	v_add_f32_e32 v48, 1.0, v48
	global_store_dwordx4 v[82:83], v[90:93], off nt
	s_nop 1
	v_rcp_f32_e32 v82, v48
	v_mul_f32_e32 v48, 0xbfb8aa3b, v79
	v_exp_f32_e32 v48, v48
	v_pk_mul_f32 v[78:79], v[80:81], v[146:147] op_sel_hi:[1,0]
	v_pk_mul_f32 v[62:63], v[62:63], v[144:145] op_sel_hi:[1,0]
	v_pk_mul_f32 v[76:77], v[78:79], v[76:77]
	v_add_f32_e32 v48, 1.0, v48
	v_rcp_f32_e32 v83, v48
	v_mul_f32_e32 v48, 0xbfb8aa3b, v78
	v_exp_f32_e32 v48, v48
	v_pk_mul_f32 v[68:69], v[68:69], v[146:147] op_sel_hi:[1,0]
	v_pk_mul_f32 v[74:75], v[74:75], v[82:83]
	v_pk_mul_f32 v[58:59], v[58:59], v[144:145] op_sel_hi:[1,0]
	v_add_f32_e32 v48, 1.0, v48
	v_rcp_f32_e32 v80, v48
	v_mul_f32_e32 v48, 0xbfb8aa3b, v79
	v_exp_f32_e32 v48, v48
	v_cvt_pk_bf16_f32 v74, v74, v75
	v_pk_mul_f32 v[58:59], v[62:63], v[58:59]
	v_pk_mul_f32 v[54:55], v[54:55], v[144:145] op_sel_hi:[1,0]
	v_add_f32_e32 v48, 1.0, v48
	v_rcp_f32_e32 v81, v48
	v_mul_f32_e32 v48, 0xbfb8aa3b, v70
	v_exp_f32_e32 v48, v48
	v_pk_mul_f32 v[60:61], v[60:61], v[144:145] op_sel_hi:[1,0]
	v_pk_mul_f32 v[76:77], v[76:77], v[80:81]
	v_pk_mul_f32 v[50:51], v[50:51], v[144:145] op_sel_hi:[1,0]
	v_add_f32_e32 v48, 1.0, v48
	v_cvt_pk_bf16_f32 v75, v76, v77
	v_rcp_f32_e32 v76, v48
	v_mul_f32_e32 v48, 0xbfb8aa3b, v71
	v_exp_f32_e32 v48, v48
	v_pk_mul_f32 v[70:71], v[72:73], v[146:147] op_sel_hi:[1,0]
	v_pk_mul_f32 v[50:51], v[54:55], v[50:51]
	v_pk_mul_f32 v[68:69], v[70:71], v[68:69]
	v_add_f32_e32 v48, 1.0, v48
	v_rcp_f32_e32 v77, v48
	v_mul_f32_e32 v48, 0xbfb8aa3b, v70
	v_exp_f32_e32 v48, v48
	v_pk_mul_f32 v[44:45], v[44:45], v[142:143] op_sel_hi:[1,0]
	v_pk_mul_f32 v[66:67], v[66:67], v[76:77]
	v_pk_mul_f32 v[40:41], v[40:41], v[142:143] op_sel_hi:[1,0]
	v_add_f32_e32 v48, 1.0, v48
	v_rcp_f32_e32 v72, v48
	v_mul_f32_e32 v48, 0xbfb8aa3b, v71
	v_exp_f32_e32 v48, v48
	v_cvt_pk_bf16_f32 v76, v66, v67
	v_pk_mul_f32 v[40:41], v[44:45], v[40:41]
	v_pk_mul_f32 v[52:53], v[52:53], v[144:145] op_sel_hi:[1,0]
	v_add_f32_e32 v48, 1.0, v48
	v_rcp_f32_e32 v73, v48
	v_add_u32_e32 v48, 0x21000, v114
	v_lshl_add_u64 v[66:67], v[48:49], 1, s[12:13]
	v_mul_f32_e32 v48, 0xbfb8aa3b, v62
	v_exp_f32_e32 v48, v48
	v_pk_mul_f32 v[68:69], v[68:69], v[72:73]
	v_pk_mul_f32 v[42:43], v[42:43], v[142:143] op_sel_hi:[1,0]
	v_cvt_pk_bf16_f32 v77, v68, v69
	v_add_f32_e32 v48, 1.0, v48
	global_store_dwordx4 v[66:67], v[74:77], off nt
	s_nop 1
	v_rcp_f32_e32 v66, v48
	v_mul_f32_e32 v48, 0xbfb8aa3b, v63
	v_exp_f32_e32 v48, v48
	v_pk_mul_f32 v[62:63], v[64:65], v[144:145] op_sel_hi:[1,0]
	v_pk_mul_f32 v[36:37], v[36:37], v[142:143] op_sel_hi:[1,0]
	v_pk_mul_f32 v[60:61], v[62:63], v[60:61]
	v_add_f32_e32 v48, 1.0, v48
	v_rcp_f32_e32 v67, v48
	v_mul_f32_e32 v48, 0xbfb8aa3b, v62
	v_exp_f32_e32 v48, v48
	v_pk_mul_f32 v[32:33], v[32:33], v[142:143] op_sel_hi:[1,0]
	v_pk_mul_f32 v[58:59], v[58:59], v[66:67]
	v_pk_mul_f32 v[32:33], v[36:37], v[32:33]
	v_add_f32_e32 v48, 1.0, v48
	v_rcp_f32_e32 v64, v48
	v_mul_f32_e32 v48, 0xbfb8aa3b, v63
	v_exp_f32_e32 v48, v48
	v_cvt_pk_bf16_f32 v58, v58, v59
	v_pk_mul_f32 v[34:35], v[34:35], v[142:143] op_sel_hi:[1,0]
	v_pk_mul_f32 v[28:29], v[28:29], v[140:141] op_sel_hi:[1,0]
	v_add_f32_e32 v48, 1.0, v48
	v_rcp_f32_e32 v65, v48
	v_mul_f32_e32 v48, 0xbfb8aa3b, v54
	v_exp_f32_e32 v48, v48
	v_pk_mul_f32 v[24:25], v[24:25], v[140:141] op_sel_hi:[1,0]
	v_pk_mul_f32 v[60:61], v[60:61], v[64:65]
	v_pk_mul_f32 v[24:25], v[28:29], v[24:25]
	v_add_f32_e32 v48, 1.0, v48
	v_cvt_pk_bf16_f32 v59, v60, v61
	v_rcp_f32_e32 v60, v48
	v_mul_f32_e32 v48, 0xbfb8aa3b, v55
	v_exp_f32_e32 v48, v48
	v_pk_mul_f32 v[54:55], v[56:57], v[144:145] op_sel_hi:[1,0]
	v_pk_mul_f32 v[26:27], v[26:27], v[140:141] op_sel_hi:[1,0]
	v_pk_mul_f32 v[52:53], v[54:55], v[52:53]
	v_add_f32_e32 v48, 1.0, v48
	v_rcp_f32_e32 v61, v48
	v_mul_f32_e32 v48, 0xbfb8aa3b, v54
	v_exp_f32_e32 v48, v48
	v_pk_mul_f32 v[20:21], v[20:21], v[140:141] op_sel_hi:[1,0]
	v_pk_mul_f32 v[50:51], v[50:51], v[60:61]
	v_pk_mul_f32 v[16:17], v[16:17], v[140:141] op_sel_hi:[1,0]
	v_add_f32_e32 v48, 1.0, v48
	v_rcp_f32_e32 v56, v48
	v_mul_f32_e32 v48, 0xbfb8aa3b, v55
	v_exp_f32_e32 v48, v48
	v_cvt_pk_bf16_f32 v60, v50, v51
	v_pk_mul_f32 v[16:17], v[20:21], v[16:17]
	v_pk_mul_f32 v[18:19], v[18:19], v[140:141] op_sel_hi:[1,0]
	v_add_f32_e32 v48, 1.0, v48
	v_rcp_f32_e32 v57, v48
	v_add_u32_e32 v48, 0x58000, v114
	v_lshl_add_u64 v[50:51], v[48:49], 1, s[12:13]
	v_mul_f32_e32 v48, 0xbfb8aa3b, v44
	v_mul_f32_e32 v44, 0xbfb8aa3b, v45
	v_exp_f32_e32 v44, v44
	v_pk_mul_f32 v[52:53], v[52:53], v[56:57]
	v_exp_f32_e32 v48, v48
	v_cvt_pk_bf16_f32 v61, v52, v53
	v_add_f32_e32 v44, 1.0, v44
	global_store_dwordx4 v[50:51], v[58:61], off nt
	s_nop 1
	v_rcp_f32_e32 v51, v44
	v_pk_mul_f32 v[44:45], v[46:47], v[142:143] op_sel_hi:[1,0]
	v_add_f32_e32 v48, 1.0, v48
	v_mul_f32_e32 v46, 0xbfb8aa3b, v44
	v_pk_mul_f32 v[42:43], v[44:45], v[42:43]
	v_mul_f32_e32 v44, 0xbfb8aa3b, v45
	v_exp_f32_e32 v46, v46
	v_exp_f32_e32 v44, v44
	v_rcp_f32_e32 v50, v48
	v_add_u32_e32 v48, 0x63000, v114
	v_add_f32_e32 v46, 1.0, v46
	v_add_f32_e32 v44, 1.0, v44
	v_rcp_f32_e32 v46, v46
	v_rcp_f32_e32 v47, v44
	v_pk_mul_f32 v[40:41], v[40:41], v[50:51]
	v_pk_mul_f32 v[12:13], v[12:13], v[138:139] op_sel_hi:[1,0]
	v_cvt_pk_bf16_f32 v40, v40, v41
	v_pk_mul_f32 v[42:43], v[42:43], v[46:47]
	v_pk_mul_f32 v[8:9], v[8:9], v[138:139] op_sel_hi:[1,0]
	v_cvt_pk_bf16_f32 v41, v42, v43
	v_mul_f32_e32 v42, 0xbfb8aa3b, v36
	v_mul_f32_e32 v36, 0xbfb8aa3b, v37
	v_exp_f32_e32 v36, v36
	v_exp_f32_e32 v42, v42
	v_pk_mul_f32 v[8:9], v[12:13], v[8:9]
	v_pk_mul_f32 v[10:11], v[10:11], v[138:139] op_sel_hi:[1,0]
	v_add_f32_e32 v36, 1.0, v36
	v_rcp_f32_e32 v43, v36
	v_pk_mul_f32 v[36:37], v[38:39], v[142:143] op_sel_hi:[1,0]
	v_add_f32_e32 v42, 1.0, v42
	v_mul_f32_e32 v38, 0xbfb8aa3b, v36
	v_pk_mul_f32 v[34:35], v[36:37], v[34:35]
	v_mul_f32_e32 v36, 0xbfb8aa3b, v37
	v_exp_f32_e32 v38, v38
	v_exp_f32_e32 v36, v36
	v_rcp_f32_e32 v42, v42
	v_pk_mul_f32 v[4:5], v[4:5], v[138:139] op_sel_hi:[1,0]
	v_add_f32_e32 v38, 1.0, v38
	v_add_f32_e32 v36, 1.0, v36
	v_rcp_f32_e32 v38, v38
	v_rcp_f32_e32 v39, v36
	v_pk_mul_f32 v[32:33], v[32:33], v[42:43]
	v_pk_mul_f32 v[0:1], v[0:1], v[138:139] op_sel_hi:[1,0]
	v_cvt_pk_bf16_f32 v42, v32, v33
	v_pk_mul_f32 v[34:35], v[34:35], v[38:39]
	v_lshl_add_u64 v[32:33], v[48:49], 1, s[12:13]
	v_cvt_pk_bf16_f32 v43, v34, v35
	global_store_dwordx4 v[32:33], v[40:43], off nt
	s_nop 1
	v_mul_f32_e32 v32, 0xbfb8aa3b, v28
	v_mul_f32_e32 v28, 0xbfb8aa3b, v29
	v_exp_f32_e32 v28, v28
	v_exp_f32_e32 v32, v32
	v_add_u32_e32 v48, 0x6e000, v114
	v_pk_mul_f32 v[0:1], v[4:5], v[0:1]
	v_add_f32_e32 v28, 1.0, v28
	v_rcp_f32_e32 v33, v28
	v_pk_mul_f32 v[28:29], v[30:31], v[140:141] op_sel_hi:[1,0]
	v_add_f32_e32 v32, 1.0, v32
	v_mul_f32_e32 v30, 0xbfb8aa3b, v28
	v_pk_mul_f32 v[26:27], v[28:29], v[26:27]
	v_mul_f32_e32 v28, 0xbfb8aa3b, v29
	v_exp_f32_e32 v30, v30
	v_exp_f32_e32 v28, v28
	v_rcp_f32_e32 v32, v32
	v_pk_mul_f32 v[2:3], v[2:3], v[138:139] op_sel_hi:[1,0]
	v_add_f32_e32 v30, 1.0, v30
	v_add_f32_e32 v28, 1.0, v28
	v_rcp_f32_e32 v30, v30
	v_rcp_f32_e32 v31, v28
	v_pk_mul_f32 v[24:25], v[24:25], v[32:33]
	s_mov_b64 s[38:39], -1
	v_cvt_pk_bf16_f32 v24, v24, v25
	v_pk_mul_f32 v[26:27], v[26:27], v[30:31]
	s_andn2_b64 vcc, exec, s[48:49]
	v_cvt_pk_bf16_f32 v25, v26, v27
	v_mul_f32_e32 v26, 0xbfb8aa3b, v20
	v_mul_f32_e32 v20, 0xbfb8aa3b, v21
	v_exp_f32_e32 v20, v20
	v_exp_f32_e32 v26, v26
	v_add_f32_e32 v20, 1.0, v20
	v_rcp_f32_e32 v27, v20
	v_pk_mul_f32 v[20:21], v[22:23], v[140:141] op_sel_hi:[1,0]
	v_add_f32_e32 v26, 1.0, v26
	v_mul_f32_e32 v22, 0xbfb8aa3b, v20
	v_pk_mul_f32 v[18:19], v[20:21], v[18:19]
	v_mul_f32_e32 v20, 0xbfb8aa3b, v21
	v_exp_f32_e32 v22, v22
	v_exp_f32_e32 v20, v20
	v_rcp_f32_e32 v26, v26
	v_add_f32_e32 v22, 1.0, v22
	v_add_f32_e32 v20, 1.0, v20
	v_rcp_f32_e32 v22, v22
	v_rcp_f32_e32 v23, v20
	v_pk_mul_f32 v[16:17], v[16:17], v[26:27]
	v_pk_mul_f32 v[18:19], v[18:19], v[22:23]
	v_cvt_pk_bf16_f32 v26, v16, v17
	v_lshl_add_u64 v[16:17], v[48:49], 1, s[12:13]
	v_cvt_pk_bf16_f32 v27, v18, v19
	global_store_dwordx4 v[16:17], v[24:27], off nt
	s_nop 1
	v_mul_f32_e32 v16, 0xbfb8aa3b, v12
	v_mul_f32_e32 v12, 0xbfb8aa3b, v13
	v_exp_f32_e32 v12, v12
	v_exp_f32_e32 v16, v16
	v_add_u32_e32 v48, 0x79000, v114
	v_add_f32_e32 v12, 1.0, v12
	v_rcp_f32_e32 v17, v12
	v_pk_mul_f32 v[12:13], v[14:15], v[138:139] op_sel_hi:[1,0]
	v_add_f32_e32 v16, 1.0, v16
	v_mul_f32_e32 v14, 0xbfb8aa3b, v12
	v_pk_mul_f32 v[10:11], v[12:13], v[10:11]
	v_mul_f32_e32 v12, 0xbfb8aa3b, v13
	v_exp_f32_e32 v14, v14
	v_exp_f32_e32 v12, v12
	v_rcp_f32_e32 v16, v16
	v_add_f32_e32 v14, 1.0, v14
	v_add_f32_e32 v12, 1.0, v12
	v_rcp_f32_e32 v14, v14
	v_rcp_f32_e32 v15, v12
	v_pk_mul_f32 v[8:9], v[8:9], v[16:17]
	v_pk_mul_f32 v[10:11], v[10:11], v[14:15]
	v_cvt_pk_bf16_f32 v8, v8, v9
	v_cvt_pk_bf16_f32 v9, v10, v11
	v_mul_f32_e32 v10, 0xbfb8aa3b, v4
	v_mul_f32_e32 v4, 0xbfb8aa3b, v5
	v_exp_f32_e32 v4, v4
	v_exp_f32_e32 v10, v10
	v_add_f32_e32 v4, 1.0, v4
	v_rcp_f32_e32 v11, v4
	v_pk_mul_f32 v[4:5], v[6:7], v[138:139] op_sel_hi:[1,0]
	v_add_f32_e32 v10, 1.0, v10
	v_mul_f32_e32 v6, 0xbfb8aa3b, v4
	v_pk_mul_f32 v[2:3], v[4:5], v[2:3]
	v_mul_f32_e32 v4, 0xbfb8aa3b, v5
	v_exp_f32_e32 v6, v6
	v_exp_f32_e32 v4, v4
	v_rcp_f32_e32 v10, v10
	v_add_f32_e32 v6, 1.0, v6
	v_add_f32_e32 v4, 1.0, v4
	v_rcp_f32_e32 v6, v6
	v_rcp_f32_e32 v7, v4
	v_pk_mul_f32 v[0:1], v[0:1], v[10:11]
	v_pk_mul_f32 v[2:3], v[2:3], v[6:7]
	v_cvt_pk_bf16_f32 v10, v0, v1
	v_cvt_pk_bf16_f32 v11, v2, v3
	v_lshl_add_u64 v[0:1], v[48:49], 1, s[12:13]
	global_store_dwordx4 v[0:1], v[8:11], off nt
	s_nop 1
	s_cbranch_vccnz .LBB0_244
	s_andn2_b64 vcc, exec, s[40:41]
	s_cbranch_vccnz .LBB0_243
	s_barrier
	s_branch .LBB0_243

.Lrs_done2:
	v_pk_mul_f32 v[126:127], v[126:127], v[150:151] op_sel_hi:[1,0]
	v_pk_mul_f32 v[122:123], v[122:123], v[150:151] op_sel_hi:[1,0]
	v_pk_mul_f32 v[124:125], v[124:125], v[150:151] op_sel_hi:[1,0]
	v_pk_mul_f32 v[122:123], v[126:127], v[122:123]
	v_mul_f32_e32 v139, 0xbfb8aa3b, v126
	v_mul_f32_e32 v126, 0xbfb8aa3b, v127
	v_exp_f32_e32 v126, v126
	v_exp_f32_e32 v139, v139
	v_pk_mul_f32 v[118:119], v[118:119], v[150:151] op_sel_hi:[1,0]
	v_pk_mul_f32 v[114:115], v[114:115], v[150:151] op_sel_hi:[1,0]
	v_add_f32_e32 v126, 1.0, v126
	v_rcp_f32_e32 v157, v126
	v_pk_mul_f32 v[126:127], v[128:129], v[150:151] op_sel_hi:[1,0]
	v_add_f32_e32 v139, 1.0, v139
	v_mul_f32_e32 v128, 0xbfb8aa3b, v126
	v_pk_mul_f32 v[124:125], v[126:127], v[124:125]
	v_mul_f32_e32 v126, 0xbfb8aa3b, v127
	v_exp_f32_e32 v128, v128
	v_exp_f32_e32 v126, v126
	v_rcp_f32_e32 v156, v139
	v_pk_mul_f32 v[114:115], v[118:119], v[114:115]
	v_add_f32_e32 v128, 1.0, v128
	v_add_f32_e32 v126, 1.0, v126
	v_rcp_f32_e32 v128, v128
	v_rcp_f32_e32 v129, v126
	v_pk_mul_f32 v[122:123], v[122:123], v[156:157]
	v_pk_mul_f32 v[116:117], v[116:117], v[150:151] op_sel_hi:[1,0]
	v_cvt_pk_bf16_f32 v122, v122, v123
	v_pk_mul_f32 v[124:125], v[124:125], v[128:129]
	v_lshl_or_b32 v152, s18, 7, v175
	v_cvt_pk_bf16_f32 v123, v124, v125
	v_mul_f32_e32 v124, 0xbfb8aa3b, v118
	v_mul_f32_e32 v118, 0xbfb8aa3b, v119
	v_exp_f32_e32 v118, v118
	v_exp_f32_e32 v124, v124
	s_movk_i32 s6, 0xb00
	v_pk_mul_f32 v[110:111], v[110:111], v[48:49] op_sel_hi:[1,0]
	v_add_f32_e32 v118, 1.0, v118
	v_rcp_f32_e32 v125, v118
	v_pk_mul_f32 v[118:119], v[120:121], v[150:151] op_sel_hi:[1,0]
	v_add_f32_e32 v124, 1.0, v124
	v_mul_f32_e32 v120, 0xbfb8aa3b, v118
	v_pk_mul_f32 v[116:117], v[118:119], v[116:117]
	v_mul_f32_e32 v118, 0xbfb8aa3b, v119
	v_exp_f32_e32 v120, v120
	v_exp_f32_e32 v118, v118
	v_rcp_f32_e32 v124, v124
	v_pk_mul_f32 v[106:107], v[106:107], v[48:49] op_sel_hi:[1,0]
	v_add_f32_e32 v120, 1.0, v120
	v_add_f32_e32 v118, 1.0, v118
	v_rcp_f32_e32 v120, v120
	v_rcp_f32_e32 v121, v118
	v_pk_mul_f32 v[114:115], v[114:115], v[124:125]
	v_pk_mul_f32 v[106:107], v[110:111], v[106:107]
	v_cvt_pk_bf16_f32 v124, v114, v115
	v_mad_u64_u32 v[114:115], s[20:21], v177, s6, v[152:153]
	v_pk_mul_f32 v[116:117], v[116:117], v[120:121]
	v_mov_b32_e32 v115, v49
	v_cvt_pk_bf16_f32 v125, v116, v117
	v_lshl_add_u64 v[116:117], v[114:115], 1, s[12:13]
	v_mul_f32_e32 v115, 0xbfb8aa3b, v110
	v_mul_f32_e32 v110, 0xbfb8aa3b, v111
	v_exp_f32_e32 v110, v110
	global_store_dwordx4 v[116:117], v[122:125], off nt
	s_nop 1
	v_pk_mul_f32 v[108:109], v[108:109], v[48:49] op_sel_hi:[1,0]
	v_exp_f32_e32 v115, v115
	v_add_f32_e32 v110, 1.0, v110
	v_rcp_f32_e32 v117, v110
	v_pk_mul_f32 v[110:111], v[112:113], v[48:49] op_sel_hi:[1,0]
	v_add_f32_e32 v115, 1.0, v115
	v_mul_f32_e32 v112, 0xbfb8aa3b, v110
	v_pk_mul_f32 v[108:109], v[110:111], v[108:109]
	v_mul_f32_e32 v110, 0xbfb8aa3b, v111
	v_exp_f32_e32 v112, v112
	v_exp_f32_e32 v110, v110
	v_rcp_f32_e32 v116, v115
	v_pk_mul_f32 v[102:103], v[102:103], v[48:49] op_sel_hi:[1,0]
	v_add_f32_e32 v112, 1.0, v112
	v_add_f32_e32 v110, 1.0, v110
	v_rcp_f32_e32 v112, v112
	v_rcp_f32_e32 v113, v110
	v_pk_mul_f32 v[106:107], v[106:107], v[116:117]
	v_pk_mul_f32 v[98:99], v[98:99], v[48:49] op_sel_hi:[1,0]
	v_cvt_pk_bf16_f32 v106, v106, v107
	v_pk_mul_f32 v[108:109], v[108:109], v[112:113]
	v_pk_mul_f32 v[98:99], v[102:103], v[98:99]
	v_cvt_pk_bf16_f32 v107, v108, v109
	v_mul_f32_e32 v108, 0xbfb8aa3b, v102
	v_mul_f32_e32 v102, 0xbfb8aa3b, v103
	v_exp_f32_e32 v102, v102
	v_exp_f32_e32 v108, v108
	v_pk_mul_f32 v[100:101], v[100:101], v[48:49] op_sel_hi:[1,0]
	v_pk_mul_f32 v[94:95], v[94:95], v[148:149] op_sel_hi:[1,0]
	v_add_f32_e32 v102, 1.0, v102
	v_rcp_f32_e32 v109, v102
	v_pk_mul_f32 v[102:103], v[104:105], v[48:49] op_sel_hi:[1,0]
	v_add_f32_e32 v108, 1.0, v108
	v_mul_f32_e32 v48, 0xbfb8aa3b, v103
	v_exp_f32_e32 v48, v48
	v_rcp_f32_e32 v108, v108
	v_mul_f32_e32 v104, 0xbfb8aa3b, v102
	v_exp_f32_e32 v104, v104
	v_add_f32_e32 v48, 1.0, v48
	v_pk_mul_f32 v[98:99], v[98:99], v[108:109]
	v_rcp_f32_e32 v105, v48
	v_add_u32_e32 v48, 0xb000, v114
	v_add_f32_e32 v104, 1.0, v104
	v_cvt_pk_bf16_f32 v108, v98, v99
	v_lshl_add_u64 v[98:99], v[48:49], 1, s[12:13]
	v_mul_f32_e32 v48, 0xbfb8aa3b, v94
	v_rcp_f32_e32 v104, v104
	v_exp_f32_e32 v48, v48
	v_pk_mul_f32 v[100:101], v[102:103], v[100:101]
	v_pk_mul_f32 v[90:91], v[90:91], v[148:149] op_sel_hi:[1,0]
	v_pk_mul_f32 v[100:101], v[100:101], v[104:105]
	v_add_f32_e32 v48, 1.0, v48
	v_cvt_pk_bf16_f32 v109, v100, v101
	global_store_dwordx4 v[98:99], v[106:109], off nt
	s_nop 1
	v_rcp_f32_e32 v98, v48
	v_mul_f32_e32 v48, 0xbfb8aa3b, v95
	v_exp_f32_e32 v48, v48
	v_pk_mul_f32 v[90:91], v[94:95], v[90:91]
	v_pk_mul_f32 v[94:95], v[96:97], v[148:149] op_sel_hi:[1,0]
	v_pk_mul_f32 v[86:87], v[86:87], v[148:149] op_sel_hi:[1,0]
	v_add_f32_e32 v48, 1.0, v48
	v_rcp_f32_e32 v99, v48
	v_mul_f32_e32 v48, 0xbfb8aa3b, v94
	v_exp_f32_e32 v48, v48
	v_pk_mul_f32 v[92:93], v[92:93], v[148:149] op_sel_hi:[1,0]
	v_pk_mul_f32 v[90:91], v[90:91], v[98:99]
	v_pk_mul_f32 v[92:93], v[94:95], v[92:93]
	v_add_f32_e32 v48, 1.0, v48
	v_rcp_f32_e32 v96, v48
	v_mul_f32_e32 v48, 0xbfb8aa3b, v95
	v_exp_f32_e32 v48, v48
	v_cvt_pk_bf16_f32 v90, v90, v91
	v_pk_mul_f32 v[82:83], v[82:83], v[148:149] op_sel_hi:[1,0]
	v_pk_mul_f32 v[78:79], v[78:79], v[146:147] op_sel_hi:[1,0]
	v_add_f32_e32 v48, 1.0, v48
	v_rcp_f32_e32 v97, v48
	v_mul_f32_e32 v48, 0xbfb8aa3b, v86
	v_exp_f32_e32 v48, v48
	v_pk_mul_f32 v[82:83], v[86:87], v[82:83]
	v_pk_mul_f32 v[92:93], v[92:93], v[96:97]
	v_pk_mul_f32 v[84:85], v[84:85], v[148:149] op_sel_hi:[1,0]
	v_add_f32_e32 v48, 1.0, v48
	v_cvt_pk_bf16_f32 v91, v92, v93
	v_rcp_f32_e32 v92, v48
	v_mul_f32_e32 v48, 0xbfb8aa3b, v87
	v_exp_f32_e32 v48, v48
	v_pk_mul_f32 v[86:87], v[88:89], v[148:149] op_sel_hi:[1,0]
	v_pk_mul_f32 v[74:75], v[74:75], v[146:147] op_sel_hi:[1,0]
	v_pk_mul_f32 v[84:85], v[86:87], v[84:85]
	v_add_f32_e32 v48, 1.0, v48
	v_rcp_f32_e32 v93, v48
	v_mul_f32_e32 v48, 0xbfb8aa3b, v86
	v_exp_f32_e32 v48, v48
	v_pk_mul_f32 v[74:75], v[78:79], v[74:75]
	v_pk_mul_f32 v[82:83], v[82:83], v[92:93]
	v_pk_mul_f32 v[70:71], v[70:71], v[146:147] op_sel_hi:[1,0]
	v_add_f32_e32 v48, 1.0, v48
	v_rcp_f32_e32 v88, v48
	v_mul_f32_e32 v48, 0xbfb8aa3b, v87
	v_exp_f32_e32 v48, v48
	v_cvt_pk_bf16_f32 v92, v82, v83
	v_pk_mul_f32 v[76:77], v[76:77], v[146:147] op_sel_hi:[1,0]
	v_pk_mul_f32 v[66:67], v[66:67], v[146:147] op_sel_hi:[1,0]
	v_add_f32_e32 v48, 1.0, v48
	v_rcp_f32_e32 v89, v48
	v_add_u32_e32 v48, 0x16000, v114
	v_lshl_add_u64 v[82:83], v[48:49], 1, s[12:13]
	v_mul_f32_e32 v48, 0xbfb8aa3b, v78
	v_exp_f32_e32 v48, v48
	v_pk_mul_f32 v[84:85], v[84:85], v[88:89]
	v_pk_mul_f32 v[66:67], v[70:71], v[66:67]
	v_cvt_pk_bf16_f32 v93, v84, v85
	v_add_f32_e32 v48, 1.0, v48
	global_store_dwordx4 v[82:83], v[90:93], off nt
	s_nop 1
	v_rcp_f32_e32 v82, v48
	v_mul_f32_e32 v48, 0xbfb8aa3b, v79
	v_exp_f32_e32 v48, v48
	v_pk_mul_f32 v[78:79], v[80:81], v[146:147] op_sel_hi:[1,0]
	v_pk_mul_f32 v[62:63], v[62:63], v[144:145] op_sel_hi:[1,0]
	v_pk_mul_f32 v[76:77], v[78:79], v[76:77]
	v_add_f32_e32 v48, 1.0, v48
	v_rcp_f32_e32 v83, v48
	v_mul_f32_e32 v48, 0xbfb8aa3b, v78
	v_exp_f32_e32 v48, v48
	v_pk_mul_f32 v[68:69], v[68:69], v[146:147] op_sel_hi:[1,0]
	v_pk_mul_f32 v[74:75], v[74:75], v[82:83]
	v_pk_mul_f32 v[58:59], v[58:59], v[144:145] op_sel_hi:[1,0]
	v_add_f32_e32 v48, 1.0, v48
	v_rcp_f32_e32 v80, v48
	v_mul_f32_e32 v48, 0xbfb8aa3b, v79
	v_exp_f32_e32 v48, v48
	v_cvt_pk_bf16_f32 v74, v74, v75
	v_pk_mul_f32 v[58:59], v[62:63], v[58:59]
	v_pk_mul_f32 v[54:55], v[54:55], v[144:145] op_sel_hi:[1,0]
	v_add_f32_e32 v48, 1.0, v48
	v_rcp_f32_e32 v81, v48
	v_mul_f32_e32 v48, 0xbfb8aa3b, v70
	v_exp_f32_e32 v48, v48
	v_pk_mul_f32 v[60:61], v[60:61], v[144:145] op_sel_hi:[1,0]
	v_pk_mul_f32 v[76:77], v[76:77], v[80:81]
	v_pk_mul_f32 v[50:51], v[50:51], v[144:145] op_sel_hi:[1,0]
	v_add_f32_e32 v48, 1.0, v48
	v_cvt_pk_bf16_f32 v75, v76, v77
	v_rcp_f32_e32 v76, v48
	v_mul_f32_e32 v48, 0xbfb8aa3b, v71
	v_exp_f32_e32 v48, v48
	v_pk_mul_f32 v[70:71], v[72:73], v[146:147] op_sel_hi:[1,0]
	v_pk_mul_f32 v[50:51], v[54:55], v[50:51]
	v_pk_mul_f32 v[68:69], v[70:71], v[68:69]
	v_add_f32_e32 v48, 1.0, v48
	v_rcp_f32_e32 v77, v48
	v_mul_f32_e32 v48, 0xbfb8aa3b, v70
	v_exp_f32_e32 v48, v48
	v_pk_mul_f32 v[44:45], v[44:45], v[142:143] op_sel_hi:[1,0]
	v_pk_mul_f32 v[66:67], v[66:67], v[76:77]
	v_pk_mul_f32 v[40:41], v[40:41], v[142:143] op_sel_hi:[1,0]
	v_add_f32_e32 v48, 1.0, v48
	v_rcp_f32_e32 v72, v48
	v_mul_f32_e32 v48, 0xbfb8aa3b, v71
	v_exp_f32_e32 v48, v48
	v_cvt_pk_bf16_f32 v76, v66, v67
	v_pk_mul_f32 v[40:41], v[44:45], v[40:41]
	v_pk_mul_f32 v[52:53], v[52:53], v[144:145] op_sel_hi:[1,0]
	v_add_f32_e32 v48, 1.0, v48
	v_rcp_f32_e32 v73, v48
	v_add_u32_e32 v48, 0x21000, v114
	v_lshl_add_u64 v[66:67], v[48:49], 1, s[12:13]
	v_mul_f32_e32 v48, 0xbfb8aa3b, v62
	v_exp_f32_e32 v48, v48
	v_pk_mul_f32 v[68:69], v[68:69], v[72:73]
	v_pk_mul_f32 v[42:43], v[42:43], v[142:143] op_sel_hi:[1,0]
	v_cvt_pk_bf16_f32 v77, v68, v69
	v_add_f32_e32 v48, 1.0, v48
	global_store_dwordx4 v[66:67], v[74:77], off nt
	s_nop 1
	v_rcp_f32_e32 v66, v48
	v_mul_f32_e32 v48, 0xbfb8aa3b, v63
	v_exp_f32_e32 v48, v48
	v_pk_mul_f32 v[62:63], v[64:65], v[144:145] op_sel_hi:[1,0]
	v_pk_mul_f32 v[36:37], v[36:37], v[142:143] op_sel_hi:[1,0]
	v_pk_mul_f32 v[60:61], v[62:63], v[60:61]
	v_add_f32_e32 v48, 1.0, v48
	v_rcp_f32_e32 v67, v48
	v_mul_f32_e32 v48, 0xbfb8aa3b, v62
	v_exp_f32_e32 v48, v48
	v_pk_mul_f32 v[32:33], v[32:33], v[142:143] op_sel_hi:[1,0]
	v_pk_mul_f32 v[58:59], v[58:59], v[66:67]
	v_pk_mul_f32 v[32:33], v[36:37], v[32:33]
	v_add_f32_e32 v48, 1.0, v48
	v_rcp_f32_e32 v64, v48
	v_mul_f32_e32 v48, 0xbfb8aa3b, v63
	v_exp_f32_e32 v48, v48
	v_cvt_pk_bf16_f32 v58, v58, v59
	v_pk_mul_f32 v[34:35], v[34:35], v[142:143] op_sel_hi:[1,0]
	v_pk_mul_f32 v[28:29], v[28:29], v[140:141] op_sel_hi:[1,0]
	v_add_f32_e32 v48, 1.0, v48
	v_rcp_f32_e32 v65, v48
	v_mul_f32_e32 v48, 0xbfb8aa3b, v54
	v_exp_f32_e32 v48, v48
	v_pk_mul_f32 v[24:25], v[24:25], v[140:141] op_sel_hi:[1,0]
	v_pk_mul_f32 v[60:61], v[60:61], v[64:65]
	v_pk_mul_f32 v[24:25], v[28:29], v[24:25]
	v_add_f32_e32 v48, 1.0, v48
	v_cvt_pk_bf16_f32 v59, v60, v61
	v_rcp_f32_e32 v60, v48
	v_mul_f32_e32 v48, 0xbfb8aa3b, v55
	v_exp_f32_e32 v48, v48
	v_pk_mul_f32 v[54:55], v[56:57], v[144:145] op_sel_hi:[1,0]
	v_pk_mul_f32 v[26:27], v[26:27], v[140:141] op_sel_hi:[1,0]
	v_pk_mul_f32 v[52:53], v[54:55], v[52:53]
	v_add_f32_e32 v48, 1.0, v48
	v_rcp_f32_e32 v61, v48
	v_mul_f32_e32 v48, 0xbfb8aa3b, v54
	v_exp_f32_e32 v48, v48
	v_pk_mul_f32 v[20:21], v[20:21], v[140:141] op_sel_hi:[1,0]
	v_pk_mul_f32 v[50:51], v[50:51], v[60:61]
	v_pk_mul_f32 v[16:17], v[16:17], v[140:141] op_sel_hi:[1,0]
	v_add_f32_e32 v48, 1.0, v48
	v_rcp_f32_e32 v56, v48
	v_mul_f32_e32 v48, 0xbfb8aa3b, v55
	v_exp_f32_e32 v48, v48
	v_cvt_pk_bf16_f32 v60, v50, v51
	v_pk_mul_f32 v[16:17], v[20:21], v[16:17]
	v_pk_mul_f32 v[18:19], v[18:19], v[140:141] op_sel_hi:[1,0]
	v_add_f32_e32 v48, 1.0, v48
	v_rcp_f32_e32 v57, v48
	v_add_u32_e32 v48, 0x58000, v114
	v_lshl_add_u64 v[50:51], v[48:49], 1, s[12:13]
	v_mul_f32_e32 v48, 0xbfb8aa3b, v44
	v_mul_f32_e32 v44, 0xbfb8aa3b, v45
	v_exp_f32_e32 v44, v44
	v_pk_mul_f32 v[52:53], v[52:53], v[56:57]
	v_exp_f32_e32 v48, v48
	v_cvt_pk_bf16_f32 v61, v52, v53
	v_add_f32_e32 v44, 1.0, v44
	global_store_dwordx4 v[50:51], v[58:61], off nt
	s_nop 1
	v_rcp_f32_e32 v51, v44
	v_pk_mul_f32 v[44:45], v[46:47], v[142:143] op_sel_hi:[1,0]
	v_add_f32_e32 v48, 1.0, v48
	v_mul_f32_e32 v46, 0xbfb8aa3b, v44
	v_pk_mul_f32 v[42:43], v[44:45], v[42:43]
	v_mul_f32_e32 v44, 0xbfb8aa3b, v45
	v_exp_f32_e32 v46, v46
	v_exp_f32_e32 v44, v44
	v_rcp_f32_e32 v50, v48
	v_add_u32_e32 v48, 0x63000, v114
	v_add_f32_e32 v46, 1.0, v46
	v_add_f32_e32 v44, 1.0, v44
	v_rcp_f32_e32 v46, v46
	v_rcp_f32_e32 v47, v44
	v_pk_mul_f32 v[40:41], v[40:41], v[50:51]
	v_pk_mul_f32 v[12:13], v[12:13], v[138:139] op_sel_hi:[1,0]
	v_cvt_pk_bf16_f32 v40, v40, v41
	v_pk_mul_f32 v[42:43], v[42:43], v[46:47]
	v_pk_mul_f32 v[8:9], v[8:9], v[138:139] op_sel_hi:[1,0]
	v_cvt_pk_bf16_f32 v41, v42, v43
	v_mul_f32_e32 v42, 0xbfb8aa3b, v36
	v_mul_f32_e32 v36, 0xbfb8aa3b, v37
	v_exp_f32_e32 v36, v36
	v_exp_f32_e32 v42, v42
	v_pk_mul_f32 v[8:9], v[12:13], v[8:9]
	v_pk_mul_f32 v[10:11], v[10:11], v[138:139] op_sel_hi:[1,0]
	v_add_f32_e32 v36, 1.0, v36
	v_rcp_f32_e32 v43, v36
	v_pk_mul_f32 v[36:37], v[38:39], v[142:143] op_sel_hi:[1,0]
	v_add_f32_e32 v42, 1.0, v42
	v_mul_f32_e32 v38, 0xbfb8aa3b, v36
	v_pk_mul_f32 v[34:35], v[36:37], v[34:35]
	v_mul_f32_e32 v36, 0xbfb8aa3b, v37
	v_exp_f32_e32 v38, v38
	v_exp_f32_e32 v36, v36
	v_rcp_f32_e32 v42, v42
	v_pk_mul_f32 v[4:5], v[4:5], v[138:139] op_sel_hi:[1,0]
	v_add_f32_e32 v38, 1.0, v38
	v_add_f32_e32 v36, 1.0, v36
	v_rcp_f32_e32 v38, v38
	v_rcp_f32_e32 v39, v36
	v_pk_mul_f32 v[32:33], v[32:33], v[42:43]
	v_pk_mul_f32 v[0:1], v[0:1], v[138:139] op_sel_hi:[1,0]
	v_cvt_pk_bf16_f32 v42, v32, v33
	v_pk_mul_f32 v[34:35], v[34:35], v[38:39]
	v_lshl_add_u64 v[32:33], v[48:49], 1, s[12:13]
	v_cvt_pk_bf16_f32 v43, v34, v35
	global_store_dwordx4 v[32:33], v[40:43], off nt
	s_nop 1
	v_mul_f32_e32 v32, 0xbfb8aa3b, v28
	v_mul_f32_e32 v28, 0xbfb8aa3b, v29
	v_exp_f32_e32 v28, v28
	v_exp_f32_e32 v32, v32
	v_add_u32_e32 v48, 0x6e000, v114
	v_pk_mul_f32 v[0:1], v[4:5], v[0:1]
	v_add_f32_e32 v28, 1.0, v28
	v_rcp_f32_e32 v33, v28
	v_pk_mul_f32 v[28:29], v[30:31], v[140:141] op_sel_hi:[1,0]
	v_add_f32_e32 v32, 1.0, v32
	v_mul_f32_e32 v30, 0xbfb8aa3b, v28
	v_pk_mul_f32 v[26:27], v[28:29], v[26:27]
	v_mul_f32_e32 v28, 0xbfb8aa3b, v29
	v_exp_f32_e32 v30, v30
	v_exp_f32_e32 v28, v28
	v_rcp_f32_e32 v32, v32
	v_pk_mul_f32 v[2:3], v[2:3], v[138:139] op_sel_hi:[1,0]
	v_add_f32_e32 v30, 1.0, v30
	v_add_f32_e32 v28, 1.0, v28
	v_rcp_f32_e32 v30, v30
	v_rcp_f32_e32 v31, v28
	v_pk_mul_f32 v[24:25], v[24:25], v[32:33]
	s_mov_b64 s[38:39], -1
	v_cvt_pk_bf16_f32 v24, v24, v25
	v_pk_mul_f32 v[26:27], v[26:27], v[30:31]
	s_andn2_b64 vcc, exec, s[46:47]
	v_cvt_pk_bf16_f32 v25, v26, v27
	v_mul_f32_e32 v26, 0xbfb8aa3b, v20
	v_mul_f32_e32 v20, 0xbfb8aa3b, v21
	v_exp_f32_e32 v20, v20
	v_exp_f32_e32 v26, v26
	v_add_f32_e32 v20, 1.0, v20
	v_rcp_f32_e32 v27, v20
	v_pk_mul_f32 v[20:21], v[22:23], v[140:141] op_sel_hi:[1,0]
	v_add_f32_e32 v26, 1.0, v26
	v_mul_f32_e32 v22, 0xbfb8aa3b, v20
	v_pk_mul_f32 v[18:19], v[20:21], v[18:19]
	v_mul_f32_e32 v20, 0xbfb8aa3b, v21
	v_exp_f32_e32 v22, v22
	v_exp_f32_e32 v20, v20
	v_rcp_f32_e32 v26, v26
	v_add_f32_e32 v22, 1.0, v22
	v_add_f32_e32 v20, 1.0, v20
	v_rcp_f32_e32 v22, v22
	v_rcp_f32_e32 v23, v20
	v_pk_mul_f32 v[16:17], v[16:17], v[26:27]
	v_pk_mul_f32 v[18:19], v[18:19], v[22:23]
	v_cvt_pk_bf16_f32 v26, v16, v17
	v_lshl_add_u64 v[16:17], v[48:49], 1, s[12:13]
	v_cvt_pk_bf16_f32 v27, v18, v19
	global_store_dwordx4 v[16:17], v[24:27], off nt
	s_nop 1
	v_mul_f32_e32 v16, 0xbfb8aa3b, v12
	v_mul_f32_e32 v12, 0xbfb8aa3b, v13
	v_exp_f32_e32 v12, v12
	v_exp_f32_e32 v16, v16
	v_add_u32_e32 v48, 0x79000, v114
	v_add_f32_e32 v12, 1.0, v12
	v_rcp_f32_e32 v17, v12
	v_pk_mul_f32 v[12:13], v[14:15], v[138:139] op_sel_hi:[1,0]
	v_add_f32_e32 v16, 1.0, v16
	v_mul_f32_e32 v14, 0xbfb8aa3b, v12
	v_pk_mul_f32 v[10:11], v[12:13], v[10:11]
	v_mul_f32_e32 v12, 0xbfb8aa3b, v13
	v_exp_f32_e32 v14, v14
	v_exp_f32_e32 v12, v12
	v_rcp_f32_e32 v16, v16
	v_add_f32_e32 v14, 1.0, v14
	v_add_f32_e32 v12, 1.0, v12
	v_rcp_f32_e32 v14, v14
	v_rcp_f32_e32 v15, v12
	v_pk_mul_f32 v[8:9], v[8:9], v[16:17]
	v_pk_mul_f32 v[10:11], v[10:11], v[14:15]
	v_cvt_pk_bf16_f32 v8, v8, v9
	v_cvt_pk_bf16_f32 v9, v10, v11
	v_mul_f32_e32 v10, 0xbfb8aa3b, v4
	v_mul_f32_e32 v4, 0xbfb8aa3b, v5
	v_exp_f32_e32 v4, v4
	v_exp_f32_e32 v10, v10
	v_add_f32_e32 v4, 1.0, v4
	v_rcp_f32_e32 v11, v4
	v_pk_mul_f32 v[4:5], v[6:7], v[138:139] op_sel_hi:[1,0]
	v_add_f32_e32 v10, 1.0, v10
	v_mul_f32_e32 v6, 0xbfb8aa3b, v4
	v_pk_mul_f32 v[2:3], v[4:5], v[2:3]
	v_mul_f32_e32 v4, 0xbfb8aa3b, v5
	v_exp_f32_e32 v6, v6
	v_exp_f32_e32 v4, v4
	v_rcp_f32_e32 v10, v10
	v_add_f32_e32 v6, 1.0, v6
	v_add_f32_e32 v4, 1.0, v4
	v_rcp_f32_e32 v6, v6
	v_rcp_f32_e32 v7, v4
	v_pk_mul_f32 v[0:1], v[0:1], v[10:11]
	v_pk_mul_f32 v[2:3], v[2:3], v[6:7]
	v_cvt_pk_bf16_f32 v10, v0, v1
	v_cvt_pk_bf16_f32 v11, v2, v3
	v_lshl_add_u64 v[0:1], v[48:49], 1, s[12:13]
	global_store_dwordx4 v[0:1], v[8:11], off nt
	s_nop 1
	s_cbranch_vccnz .LBB0_1407
	s_andn2_b64 vcc, exec, s[2:3]
	s_cbranch_vccnz .LBB0_1406
	s_barrier
	s_branch .LBB0_1406
